# v32: v31 + phase_prep weight conversion rewritten by hand: 64x64 tiles loaded three deep, double-buffered LDS transpose with one barrier per tile, SGPR tile bases + per-thread offsets computed once pe
# speedup vs baseline: 1.0117x; 1.0106x over previous
.Lcw_start:
	s_add_u32 s12, s6, 0xfffffec0
	s_addc_u32 s13, s7, -1
	s_mov_b32 s34, 0
	v_mov_b32_e32 v2, v234
	v_and_b32_e32 v3, 63, v2
	v_lshrrev_b32_e32 v4, 6, v2
	v_lshlrev_b32_e32 v21, 2, v4
	v_add_u32_e32 v22, 32, v21
	v_add_u32_e32 v23, 64, v21
	v_add_u32_e32 v24, 96, v21
	v_add_u32_e32 v25, 128, v21
	v_add_u32_e32 v26, 160, v21
	v_add_u32_e32 v27, 192, v21
	v_add_u32_e32 v28, 224, v21
	v_mul_u32_u24_e32 v29, 0x41, v4
	v_add_lshl_u32 v29, v29, v3, 2
	v_and_b32_e32 v31, 31, v2
	v_lshrrev_b32_e32 v32, 5, v2
	v_mul_u32_u24_e32 v30, 0x82, v31
	v_add_lshl_u32 v30, v30, v32, 2
	v_lshlrev_b32_e32 v31, 2, v31
	v_add_u32_e32 v33, 16, v32
	v_add_u32_e32 v34, 32, v32
	v_add_u32_e32 v35, 48, v32
	v_lshrrev_b32_e32 v36, 5, v32
	v_and_b32_e32 v44, 31, v32
	v_lshl_add_u32 v36, v36, 6, v44
	v_lshrrev_b32_e32 v37, 5, v33
	v_and_b32_e32 v44, 31, v33
	v_lshl_add_u32 v37, v37, 6, v44
	v_lshrrev_b32_e32 v38, 5, v34
	v_and_b32_e32 v44, 31, v34
	v_lshl_add_u32 v38, v38, 6, v44
	v_lshrrev_b32_e32 v39, 5, v35
	v_and_b32_e32 v44, 31, v35
	v_lshl_add_u32 v39, v39, 6, v44
	s_load_dwordx2 s[16:17], s[12:13], 0x18
	s_load_dwordx2 s[18:19], s[12:13], 0xc8
	s_load_dwordx2 s[26:27], s[12:13], 0x10
	s_movk_i32 s22, 36
	s_mov_b32 s23, 0x71c71c8
	s_movk_i32 s24, 576
	s_movk_i32 s25, 575
	s_mov_b32 s20, 0x90000
	s_movk_i32 s21, 0x800
	s_mov_b32 s28, 1
	s_mov_b32 s29, 0
	s_mov_b32 s30, 0
	s_waitcnt lgkmcnt(0)
	s_add_u32 s18, s18, 0x100000
	s_addc_u32 s19, s19, 0
	s_branch .Lcw_run
.Lcw_ret_0:
	s_load_dwordx2 s[16:17], s[12:13], 0x58
	s_load_dwordx2 s[18:19], s[12:13], 0xc8
	s_movk_i32 s22, 16
	s_mov_b32 s23, 0x10000001
	s_movk_i32 s24, 256
	s_movk_i32 s25, 255
	s_mov_b32 s20, 0x40000
	s_movk_i32 s21, 0x800
	s_mov_b32 s28, 0
	s_mov_b32 s29, 0
	s_mov_b32 s30, 1
	s_waitcnt lgkmcnt(0)
	s_add_u32 s18, s18, 0x700000
	s_addc_u32 s19, s19, 0
	s_mov_b64 s[26:27], s[16:17]
	s_branch .Lcw_run
.Lcw_ret_1:
	s_load_dwordx2 s[16:17], s[12:13], 0x80
	s_load_dwordx2 s[18:19], s[12:13], 0xc8
	s_load_dwordx2 s[26:27], s[12:13], 0x78
	s_movk_i32 s22, 88
	s_mov_b32 s23, 0x2e8ba2f
	s_movk_i32 s24, 1408
	s_movk_i32 s25, 1407
	s_mov_b32 s20, 0x160000
	s_movk_i32 s21, 0x800
	s_mov_b32 s28, 1
	s_mov_b32 s29, 1
	s_mov_b32 s30, 2
	s_waitcnt lgkmcnt(0)
	s_add_u32 s18, s18, 0x900000
	s_addc_u32 s19, s19, 0
	s_branch .Lcw_run
.Lcw_ret_2:
	s_load_dwordx2 s[16:17], s[12:13], 0x98
	s_load_dwordx2 s[18:19], s[12:13], 0xc8
	s_movk_i32 s22, 16
	s_mov_b32 s23, 0x10000001
	s_movk_i32 s24, 704
	s_movk_i32 s25, 703
	s_mov_b32 s20, 0x40000
	s_movk_i32 s21, 0x1600
	s_mov_b32 s28, 0
	s_mov_b32 s29, 0
	s_mov_b32 s30, 3
	s_waitcnt lgkmcnt(0)
	s_add_u32 s18, s18, 0x1400000
	s_addc_u32 s19, s19, 0
	s_mov_b64 s[26:27], s[16:17]
	s_branch .Lcw_run
.Lcw_ret_3:
	s_load_dwordx2 s[16:17], s[12:13], 0xa8
	s_load_dwordx2 s[18:19], s[12:13], 0xc8
	s_load_dwordx2 s[26:27], s[12:13], 0xa0
	s_movk_i32 s22, 16
	s_mov_b32 s23, 0x10000001
	s_movk_i32 s24, 256
	s_movk_i32 s25, 255
	s_mov_b32 s20, 0x40000
	s_movk_i32 s21, 0x800
	s_mov_b32 s28, 1
	s_mov_b32 s29, 0
	s_mov_b32 s30, 4
	s_waitcnt lgkmcnt(0)
	s_add_u32 s18, s18, 0x1980000
	s_addc_u32 s19, s19, 0
	s_branch .Lcw_run
.Lcw_ret_4:
	s_load_dwordx2 s[16:17], s[12:13], 0xb0
	s_load_dwordx2 s[18:19], s[12:13], 0xc8
	s_movk_i32 s22, 16
	s_mov_b32 s23, 0x10000001
	s_movk_i32 s24, 64
	s_movk_i32 s25, 63
	s_mov_b32 s20, 0x40000
	s_movk_i32 s21, 0x200
	s_mov_b32 s28, 0
	s_mov_b32 s29, 0
	s_mov_b32 s30, 5
	s_waitcnt lgkmcnt(0)
	s_add_u32 s18, s18, 0x1b80000
	s_addc_u32 s19, s19, 0
	s_mov_b64 s[26:27], s[16:17]
	s_branch .Lcw_run
.Lcw_ret_5:
	s_load_dwordx2 s[16:17], s[12:13], 0x60
	s_load_dwordx2 s[18:19], s[12:13], 0xc8
	s_load_dwordx2 s[26:27], s[12:13], 0x10
	s_movk_i32 s22, 48
	s_mov_b32 s23, 0x5555556
	s_movk_i32 s24, 768
	s_movk_i32 s25, 767
	s_mov_b32 s20, 0xc0000
	s_movk_i32 s21, 0x800
	s_mov_b32 s28, 1
	s_mov_b32 s29, 0
	s_mov_b32 s30, 6
	s_waitcnt lgkmcnt(0)
	s_add_u32 s18, s18, 0x1c00000
	s_addc_u32 s19, s19, 0
	s_add_u32 s26, s26, 0x1000
	s_addc_u32 s27, s27, 0
	s_branch .Lcw_run
.Lcw_ret_6:
	s_load_dwordx2 s[16:17], s[12:13], 0x70
	s_load_dwordx2 s[18:19], s[12:13], 0xc8
	s_movk_i32 s22, 16
	s_mov_b32 s23, 0x10000001
	s_movk_i32 s24, 256
	s_movk_i32 s25, 255
	s_mov_b32 s20, 0x40000
	s_movk_i32 s21, 0x800
	s_mov_b32 s28, 0
	s_mov_b32 s29, 0
	s_mov_b32 s30, 7
	s_waitcnt lgkmcnt(0)
	s_add_u32 s18, s18, 0x2200000
	s_addc_u32 s19, s19, 0
	s_mov_b64 s[26:27], s[16:17]
	s_branch .Lcw_run
.Lcw_ret_7:
	s_load_dwordx2 s[16:17], s[12:13], 0x80
	s_load_dwordx2 s[18:19], s[12:13], 0xc8
	s_load_dwordx2 s[26:27], s[12:13], 0x78
	s_movk_i32 s22, 88
	s_mov_b32 s23, 0x2e8ba2f
	s_movk_i32 s24, 1408
	s_movk_i32 s25, 1407
	s_mov_b32 s20, 0x160000
	s_movk_i32 s21, 0x800
	s_mov_b32 s28, 1
	s_mov_b32 s29, 1
	s_mov_b32 s30, 8
	s_waitcnt lgkmcnt(0)
	s_add_u32 s16, s16, 0x1600000
	s_addc_u32 s17, s17, 0
	s_add_u32 s18, s18, 0x2400000
	s_addc_u32 s19, s19, 0
	s_add_u32 s26, s26, 0x1000
	s_addc_u32 s27, s27, 0
	s_branch .Lcw_run
.Lcw_ret_8:
	s_load_dwordx2 s[16:17], s[12:13], 0x98
	s_load_dwordx2 s[18:19], s[12:13], 0xc8
	s_movk_i32 s22, 16
	s_mov_b32 s23, 0x10000001
	s_movk_i32 s24, 704
	s_movk_i32 s25, 703
	s_mov_b32 s20, 0x40000
	s_movk_i32 s21, 0x1600
	s_mov_b32 s28, 0
	s_mov_b32 s29, 0
	s_mov_b32 s30, 9
	s_waitcnt lgkmcnt(0)
	s_add_u32 s16, s16, 0xb00000
	s_addc_u32 s17, s17, 0
	s_add_u32 s18, s18, 0x2f00000
	s_addc_u32 s19, s19, 0
	s_mov_b64 s[26:27], s[16:17]
	s_branch .Lcw_run
.Lcw_ret_9:
	s_load_dwordx2 s[16:17], s[12:13], 0xa8
	s_load_dwordx2 s[18:19], s[12:13], 0xc8
	s_load_dwordx2 s[26:27], s[12:13], 0xa0
	s_movk_i32 s22, 16
	s_mov_b32 s23, 0x10000001
	s_movk_i32 s24, 256
	s_movk_i32 s25, 255
	s_mov_b32 s20, 0x40000
	s_movk_i32 s21, 0x800
	s_mov_b32 s28, 1
	s_mov_b32 s29, 0
	s_mov_b32 s30, 10
	s_waitcnt lgkmcnt(0)
	s_add_u32 s16, s16, 0x400000
	s_addc_u32 s17, s17, 0
	s_add_u32 s18, s18, 0x3480000
	s_addc_u32 s19, s19, 0
	s_add_u32 s26, s26, 0x1000
	s_addc_u32 s27, s27, 0
	s_branch .Lcw_run
.Lcw_ret_10:
	s_load_dwordx2 s[16:17], s[12:13], 0xb0
	s_load_dwordx2 s[18:19], s[12:13], 0xc8
	s_movk_i32 s22, 16
	s_mov_b32 s23, 0x10000001
	s_movk_i32 s24, 64
	s_movk_i32 s25, 63
	s_mov_b32 s20, 0x40000
	s_movk_i32 s21, 0x200
	s_mov_b32 s28, 0
	s_mov_b32 s29, 0
	s_mov_b32 s30, 11
	s_waitcnt lgkmcnt(0)
	s_add_u32 s16, s16, 0x100000
	s_addc_u32 s17, s17, 0
	s_add_u32 s18, s18, 0x3680000
	s_addc_u32 s19, s19, 0
	s_mov_b64 s[26:27], s[16:17]
	s_branch .Lcw_run
.Lcw_ret_11:
	s_load_dwordx2 s[16:17], s[12:13], 0x18
	s_load_dwordx2 s[18:19], s[12:13], 0xc8
	s_load_dwordx2 s[26:27], s[12:13], 0x10
	s_movk_i32 s22, 36
	s_mov_b32 s23, 0x71c71c8
	s_movk_i32 s24, 576
	s_movk_i32 s25, 575
	s_mov_b32 s20, 0x90000
	s_movk_i32 s21, 0x800
	s_mov_b32 s28, 1
	s_mov_b32 s29, 0
	s_mov_b32 s30, 12
	s_waitcnt lgkmcnt(0)
	s_add_u32 s16, s16, 0x900000
	s_addc_u32 s17, s17, 0
	s_add_u32 s18, s18, 0x3700000
	s_addc_u32 s19, s19, 0
	s_add_u32 s26, s26, 0x2000
	s_addc_u32 s27, s27, 0
	s_branch .Lcw_run
.Lcw_ret_12:
	s_load_dwordx2 s[16:17], s[12:13], 0x58
	s_load_dwordx2 s[18:19], s[12:13], 0xc8
	s_movk_i32 s22, 16
	s_mov_b32 s23, 0x10000001
	s_movk_i32 s24, 256
	s_movk_i32 s25, 255
	s_mov_b32 s20, 0x40000
	s_movk_i32 s21, 0x800
	s_mov_b32 s28, 0
	s_mov_b32 s29, 0
	s_mov_b32 s30, 13
	s_waitcnt lgkmcnt(0)
	s_add_u32 s16, s16, 0x400000
	s_addc_u32 s17, s17, 0
	s_add_u32 s18, s18, 0x3d00000
	s_addc_u32 s19, s19, 0
	s_mov_b64 s[26:27], s[16:17]
	s_branch .Lcw_run
.Lcw_ret_13:
	s_load_dwordx2 s[16:17], s[12:13], 0x80
	s_load_dwordx2 s[18:19], s[12:13], 0xc8
	s_load_dwordx2 s[26:27], s[12:13], 0x78
	s_movk_i32 s22, 88
	s_mov_b32 s23, 0x2e8ba2f
	s_movk_i32 s24, 1408
	s_movk_i32 s25, 1407
	s_mov_b32 s20, 0x160000
	s_movk_i32 s21, 0x800
	s_mov_b32 s28, 1
	s_mov_b32 s29, 1
	s_mov_b32 s30, 14
	s_waitcnt lgkmcnt(0)
	s_add_u32 s16, s16, 0x2c00000
	s_addc_u32 s17, s17, 0
	s_add_u32 s18, s18, 0x3f00000
	s_addc_u32 s19, s19, 0
	s_add_u32 s26, s26, 0x2000
	s_addc_u32 s27, s27, 0
	s_branch .Lcw_run
.Lcw_ret_14:
	s_load_dwordx2 s[16:17], s[12:13], 0x98
	s_load_dwordx2 s[18:19], s[12:13], 0xc8
	s_movk_i32 s22, 16
	s_mov_b32 s23, 0x10000001
	s_movk_i32 s24, 704
	s_movk_i32 s25, 703
	s_mov_b32 s20, 0x40000
	s_movk_i32 s21, 0x1600
	s_mov_b32 s28, 0
	s_mov_b32 s29, 0
	s_mov_b32 s30, 15
	s_waitcnt lgkmcnt(0)
	s_add_u32 s16, s16, 0x1600000
	s_addc_u32 s17, s17, 0
	s_add_u32 s18, s18, 0x4a00000
	s_addc_u32 s19, s19, 0
	s_mov_b64 s[26:27], s[16:17]
	s_branch .Lcw_run
.Lcw_ret_15:
	s_load_dwordx2 s[16:17], s[12:13], 0xa8
	s_load_dwordx2 s[18:19], s[12:13], 0xc8
	s_load_dwordx2 s[26:27], s[12:13], 0xa0
	s_movk_i32 s22, 16
	s_mov_b32 s23, 0x10000001
	s_movk_i32 s24, 256
	s_movk_i32 s25, 255
	s_mov_b32 s20, 0x40000
	s_movk_i32 s21, 0x800
	s_mov_b32 s28, 1
	s_mov_b32 s29, 0
	s_mov_b32 s30, 16
	s_waitcnt lgkmcnt(0)
	s_add_u32 s16, s16, 0x800000
	s_addc_u32 s17, s17, 0
	s_add_u32 s18, s18, 0x4f80000
	s_addc_u32 s19, s19, 0
	s_add_u32 s26, s26, 0x2000
	s_addc_u32 s27, s27, 0
	s_branch .Lcw_run
.Lcw_ret_16:
	s_load_dwordx2 s[16:17], s[12:13], 0xb0
	s_load_dwordx2 s[18:19], s[12:13], 0xc8
	s_movk_i32 s22, 16
	s_mov_b32 s23, 0x10000001
	s_movk_i32 s24, 64
	s_movk_i32 s25, 63
	s_mov_b32 s20, 0x40000
	s_movk_i32 s21, 0x200
	s_mov_b32 s28, 0
	s_mov_b32 s29, 0
	s_mov_b32 s30, 17
	s_waitcnt lgkmcnt(0)
	s_add_u32 s16, s16, 0x200000
	s_addc_u32 s17, s17, 0
	s_add_u32 s18, s18, 0x5180000
	s_addc_u32 s19, s19, 0
	s_mov_b64 s[26:27], s[16:17]
	s_branch .Lcw_run
.Lcw_ret_17:
	s_load_dwordx2 s[16:17], s[12:13], 0x60
	s_load_dwordx2 s[18:19], s[12:13], 0xc8
	s_load_dwordx2 s[26:27], s[12:13], 0x10
	s_movk_i32 s22, 48
	s_mov_b32 s23, 0x5555556
	s_movk_i32 s24, 768
	s_movk_i32 s25, 767
	s_mov_b32 s20, 0xc0000
	s_movk_i32 s21, 0x800
	s_mov_b32 s28, 1
	s_mov_b32 s29, 0
	s_mov_b32 s30, 18
	s_waitcnt lgkmcnt(0)
	s_add_u32 s16, s16, 0xc00000
	s_addc_u32 s17, s17, 0
	s_add_u32 s18, s18, 0x5200000
	s_addc_u32 s19, s19, 0
	s_add_u32 s26, s26, 0x3000
	s_addc_u32 s27, s27, 0
	s_branch .Lcw_run
.Lcw_ret_18:
	s_load_dwordx2 s[16:17], s[12:13], 0x70
	s_load_dwordx2 s[18:19], s[12:13], 0xc8
	s_movk_i32 s22, 16
	s_mov_b32 s23, 0x10000001
	s_movk_i32 s24, 256
	s_movk_i32 s25, 255
	s_mov_b32 s20, 0x40000
	s_movk_i32 s21, 0x800
	s_mov_b32 s28, 0
	s_mov_b32 s29, 0
	s_mov_b32 s30, 19
	s_waitcnt lgkmcnt(0)
	s_add_u32 s16, s16, 0x400000
	s_addc_u32 s17, s17, 0
	s_add_u32 s18, s18, 0x5800000
	s_addc_u32 s19, s19, 0
	s_mov_b64 s[26:27], s[16:17]
	s_branch .Lcw_run
.Lcw_ret_19:
	s_load_dwordx2 s[16:17], s[12:13], 0x80
	s_load_dwordx2 s[18:19], s[12:13], 0xc8
	s_load_dwordx2 s[26:27], s[12:13], 0x78
	s_movk_i32 s22, 88
	s_mov_b32 s23, 0x2e8ba2f
	s_movk_i32 s24, 1408
	s_movk_i32 s25, 1407
	s_mov_b32 s20, 0x160000
	s_movk_i32 s21, 0x800
	s_mov_b32 s28, 1
	s_mov_b32 s29, 1
	s_mov_b32 s30, 20
	s_waitcnt lgkmcnt(0)
	s_add_u32 s16, s16, 0x4200000
	s_addc_u32 s17, s17, 0
	s_add_u32 s18, s18, 0x5a00000
	s_addc_u32 s19, s19, 0
	s_add_u32 s26, s26, 0x3000
	s_addc_u32 s27, s27, 0
	s_branch .Lcw_run
.Lcw_ret_20:
	s_load_dwordx2 s[16:17], s[12:13], 0x98
	s_load_dwordx2 s[18:19], s[12:13], 0xc8
	s_movk_i32 s22, 16
	s_mov_b32 s23, 0x10000001
	s_movk_i32 s24, 704
	s_movk_i32 s25, 703
	s_mov_b32 s20, 0x40000
	s_movk_i32 s21, 0x1600
	s_mov_b32 s28, 0
	s_mov_b32 s29, 0
	s_mov_b32 s30, 21
	s_waitcnt lgkmcnt(0)
	s_add_u32 s16, s16, 0x2100000
	s_addc_u32 s17, s17, 0
	s_add_u32 s18, s18, 0x6500000
	s_addc_u32 s19, s19, 0
	s_mov_b64 s[26:27], s[16:17]
	s_branch .Lcw_run
.Lcw_ret_21:
	s_load_dwordx2 s[16:17], s[12:13], 0xa8
	s_load_dwordx2 s[18:19], s[12:13], 0xc8
	s_load_dwordx2 s[26:27], s[12:13], 0xa0
	s_movk_i32 s22, 16
	s_mov_b32 s23, 0x10000001
	s_movk_i32 s24, 256
	s_movk_i32 s25, 255
	s_mov_b32 s20, 0x40000
	s_movk_i32 s21, 0x800
	s_mov_b32 s28, 1
	s_mov_b32 s29, 0
	s_mov_b32 s30, 22
	s_waitcnt lgkmcnt(0)
	s_add_u32 s16, s16, 0xc00000
	s_addc_u32 s17, s17, 0
	s_add_u32 s18, s18, 0x6a80000
	s_addc_u32 s19, s19, 0
	s_add_u32 s26, s26, 0x3000
	s_addc_u32 s27, s27, 0
	s_branch .Lcw_run
.Lcw_ret_22:
	s_load_dwordx2 s[16:17], s[12:13], 0xb0
	s_load_dwordx2 s[18:19], s[12:13], 0xc8
	s_movk_i32 s22, 16
	s_mov_b32 s23, 0x10000001
	s_movk_i32 s24, 64
	s_movk_i32 s25, 63
	s_mov_b32 s20, 0x40000
	s_movk_i32 s21, 0x200
	s_mov_b32 s28, 0
	s_mov_b32 s29, 0
	s_mov_b32 s30, 23
	s_waitcnt lgkmcnt(0)
	s_add_u32 s16, s16, 0x300000
	s_addc_u32 s17, s17, 0
	s_add_u32 s18, s18, 0x6c80000
	s_addc_u32 s19, s19, 0
	s_mov_b64 s[26:27], s[16:17]
	s_branch .Lcw_run
.Lcw_ret_23:
	s_waitcnt lgkmcnt(0)
	s_barrier
	s_branch .LBB0_99
.Lcw_run:
	s_cmp_ge_u32 s2, s24
	s_cbranch_scc1 .Lcw_done
	s_lshr_b32 s35, s20, 8
	v_mul_lo_u32 v13, v4, s35
	v_add_lshl_u32 v13, v13, v3, 2
	s_lshl_b32 s35, s35, 5
	v_add_u32_e32 v14, s35, v13
	v_add_u32_e32 v15, s35, v14
	v_add_u32_e32 v16, s35, v15
	v_add_u32_e32 v17, s35, v16
	v_add_u32_e32 v18, s35, v17
	v_add_u32_e32 v19, s35, v18
	v_add_u32_e32 v20, s35, v19
	s_cmp_lg_u32 s29, 0
	s_cbranch_scc1 .Lcw_permrows
	v_mul_lo_u32 v40, v32, s21
	v_add_u32_e32 v40, v40, v31
	v_mul_lo_u32 v41, v33, s21
	v_add_u32_e32 v41, v41, v31
	v_mul_lo_u32 v42, v34, s21
	v_add_u32_e32 v42, v42, v31
	v_mul_lo_u32 v43, v35, s21
	v_add_u32_e32 v43, v43, v31
	s_branch .Lcw_rows_done
.Lcw_permrows:
	v_mul_lo_u32 v40, v36, s21
	v_add_u32_e32 v40, v40, v31
	v_mul_lo_u32 v41, v37, s21
	v_add_u32_e32 v41, v41, v31
	v_mul_lo_u32 v42, v38, s21
	v_add_u32_e32 v42, v42, v31
	v_mul_lo_u32 v43, v39, s21
	v_add_u32_e32 v43, v43, v31
.Lcw_rows_done:
	s_mov_b32 s31, s2
	s_mov_b32 s32, s2
	s_min_u32 s54, s31, s25
	s_mul_hi_u32 s55, s54, s23
	s_mul_i32 s56, s55, s22
	s_sub_u32 s56, s54, s56
	s_mul_i32 s57, s55, s20
	s_lshl_b32 s56, s56, 8
	s_add_u32 s57, s57, s56
	s_add_u32 s48, s16, s57
	s_addc_u32 s49, s17, 0
	s_lshl_b32 s55, s55, 8
	s_add_u32 s50, s26, s55
	s_addc_u32 s51, s27, 0
	global_load_dword v64, v13, s[48:49]
	global_load_dword v65, v14, s[48:49]
	global_load_dword v66, v15, s[48:49]
	global_load_dword v67, v16, s[48:49]
	global_load_dword v68, v17, s[48:49]
	global_load_dword v69, v18, s[48:49]
	global_load_dword v70, v19, s[48:49]
	global_load_dword v71, v20, s[48:49]
	global_load_dword v88, v21, s[50:51]
	global_load_dword v89, v22, s[50:51]
	global_load_dword v90, v23, s[50:51]
	global_load_dword v91, v24, s[50:51]
	global_load_dword v92, v25, s[50:51]
	global_load_dword v93, v26, s[50:51]
	global_load_dword v94, v27, s[50:51]
	global_load_dword v95, v28, s[50:51]
	s_addk_i32 s31, 0x100
	s_min_u32 s54, s31, s25
	s_mul_hi_u32 s55, s54, s23
	s_mul_i32 s56, s55, s22
	s_sub_u32 s56, s54, s56
	s_mul_i32 s57, s55, s20
	s_lshl_b32 s56, s56, 8
	s_add_u32 s57, s57, s56
	s_add_u32 s48, s16, s57
	s_addc_u32 s49, s17, 0
	s_lshl_b32 s55, s55, 8
	s_add_u32 s50, s26, s55
	s_addc_u32 s51, s27, 0
	global_load_dword v72, v13, s[48:49]
	global_load_dword v73, v14, s[48:49]
	global_load_dword v74, v15, s[48:49]
	global_load_dword v75, v16, s[48:49]
	global_load_dword v76, v17, s[48:49]
	global_load_dword v77, v18, s[48:49]
	global_load_dword v78, v19, s[48:49]
	global_load_dword v79, v20, s[48:49]
	global_load_dword v96, v21, s[50:51]
	global_load_dword v97, v22, s[50:51]
	global_load_dword v98, v23, s[50:51]
	global_load_dword v99, v24, s[50:51]
	global_load_dword v100, v25, s[50:51]
	global_load_dword v101, v26, s[50:51]
	global_load_dword v102, v27, s[50:51]
	global_load_dword v103, v28, s[50:51]
	s_addk_i32 s31, 0x100
.Lcw_loop:
	s_min_u32 s54, s31, s25
	s_mul_hi_u32 s55, s54, s23
	s_mul_i32 s56, s55, s22
	s_sub_u32 s56, s54, s56
	s_mul_i32 s57, s55, s20
	s_lshl_b32 s56, s56, 8
	s_add_u32 s57, s57, s56
	s_add_u32 s48, s16, s57
	s_addc_u32 s49, s17, 0
	s_lshl_b32 s55, s55, 8
	s_add_u32 s50, s26, s55
	s_addc_u32 s51, s27, 0
	global_load_dword v80, v13, s[48:49]
	global_load_dword v81, v14, s[48:49]
	global_load_dword v82, v15, s[48:49]
	global_load_dword v83, v16, s[48:49]
	global_load_dword v84, v17, s[48:49]
	global_load_dword v85, v18, s[48:49]
	global_load_dword v86, v19, s[48:49]
	global_load_dword v87, v20, s[48:49]
	global_load_dword v104, v21, s[50:51]
	global_load_dword v105, v22, s[50:51]
	global_load_dword v106, v23, s[50:51]
	global_load_dword v107, v24, s[50:51]
	global_load_dword v108, v25, s[50:51]
	global_load_dword v109, v26, s[50:51]
	global_load_dword v110, v27, s[50:51]
	global_load_dword v111, v28, s[50:51]
	s_addk_i32 s31, 0x100
	s_waitcnt vmcnt(32)
	s_cmp_eq_u32 s28, 0
	s_cbranch_scc1 .Lcw_nogain_0
	v_mul_f32_e32 v64, v64, v88
	v_mul_f32_e32 v65, v65, v89
	v_mul_f32_e32 v66, v66, v90
	v_mul_f32_e32 v67, v67, v91
	v_mul_f32_e32 v68, v68, v92
	v_mul_f32_e32 v69, v69, v93
	v_mul_f32_e32 v70, v70, v94
	v_mul_f32_e32 v71, v71, v95
.Lcw_nogain_0:
	v_add_u32_e32 v44, s34, v29
	v_add_u32_e32 v45, s34, v30
	ds_write_b32 v44, v64
	ds_write_b32 v44, v65 offset:2080
	ds_write_b32 v44, v66 offset:4160
	ds_write_b32 v44, v67 offset:6240
	ds_write_b32 v44, v68 offset:8320
	ds_write_b32 v44, v69 offset:10400
	ds_write_b32 v44, v70 offset:12480
	ds_write_b32 v44, v71 offset:14560
	s_mul_hi_u32 s55, s32, s23
	s_mul_i32 s56, s55, s22
	s_sub_u32 s56, s32, s56
	s_lshl_b32 s57, s56, 6
	s_cmp_eq_u32 s29, 0
	s_cbranch_scc1 .Lcw_np_0
	s_lshl_b32 s57, s56, 7
	s_cmpk_lt_u32 s56, 44
	s_cbranch_scc1 .Lcw_np_0
	s_addk_i32 s57, -5600
.Lcw_np_0:
	s_mul_i32 s57, s57, s21
	s_lshl_b32 s55, s55, 7
	s_add_u32 s57, s57, s55
	s_add_u32 s52, s18, s57
	s_addc_u32 s53, s19, 0
	s_waitcnt lgkmcnt(0)
	s_barrier
	ds_read2_b32 v[46:47], v45 offset0:0 offset1:65
	ds_read2_b32 v[48:49], v45 offset0:16 offset1:81
	ds_read2_b32 v[50:51], v45 offset0:32 offset1:97
	ds_read2_b32 v[52:53], v45 offset0:48 offset1:113
	s_waitcnt lgkmcnt(3)
	v_cvt_pk_bf16_f32 v54, v46, v47
	global_store_dword v40, v54, s[52:53]
	s_waitcnt lgkmcnt(2)
	v_cvt_pk_bf16_f32 v55, v48, v49
	global_store_dword v41, v55, s[52:53]
	s_waitcnt lgkmcnt(1)
	v_cvt_pk_bf16_f32 v56, v50, v51
	global_store_dword v42, v56, s[52:53]
	s_waitcnt lgkmcnt(0)
	v_cvt_pk_bf16_f32 v57, v52, v53
	global_store_dword v43, v57, s[52:53]
	s_xor_b32 s34, s34, 0x4100
	s_addk_i32 s32, 0x100
	s_cmp_ge_u32 s32, s24
	s_cbranch_scc1 .Lcw_done
	s_min_u32 s54, s31, s25
	s_mul_hi_u32 s55, s54, s23
	s_mul_i32 s56, s55, s22
	s_sub_u32 s56, s54, s56
	s_mul_i32 s57, s55, s20
	s_lshl_b32 s56, s56, 8
	s_add_u32 s57, s57, s56
	s_add_u32 s48, s16, s57
	s_addc_u32 s49, s17, 0
	s_lshl_b32 s55, s55, 8
	s_add_u32 s50, s26, s55
	s_addc_u32 s51, s27, 0
	global_load_dword v64, v13, s[48:49]
	global_load_dword v65, v14, s[48:49]
	global_load_dword v66, v15, s[48:49]
	global_load_dword v67, v16, s[48:49]
	global_load_dword v68, v17, s[48:49]
	global_load_dword v69, v18, s[48:49]
	global_load_dword v70, v19, s[48:49]
	global_load_dword v71, v20, s[48:49]
	global_load_dword v88, v21, s[50:51]
	global_load_dword v89, v22, s[50:51]
	global_load_dword v90, v23, s[50:51]
	global_load_dword v91, v24, s[50:51]
	global_load_dword v92, v25, s[50:51]
	global_load_dword v93, v26, s[50:51]
	global_load_dword v94, v27, s[50:51]
	global_load_dword v95, v28, s[50:51]
	s_addk_i32 s31, 0x100
	s_waitcnt vmcnt(32)
	s_cmp_eq_u32 s28, 0
	s_cbranch_scc1 .Lcw_nogain_1
	v_mul_f32_e32 v72, v72, v96
	v_mul_f32_e32 v73, v73, v97
	v_mul_f32_e32 v74, v74, v98
	v_mul_f32_e32 v75, v75, v99
	v_mul_f32_e32 v76, v76, v100
	v_mul_f32_e32 v77, v77, v101
	v_mul_f32_e32 v78, v78, v102
	v_mul_f32_e32 v79, v79, v103
.Lcw_nogain_1:
	v_add_u32_e32 v44, s34, v29
	v_add_u32_e32 v45, s34, v30
	ds_write_b32 v44, v72
	ds_write_b32 v44, v73 offset:2080
	ds_write_b32 v44, v74 offset:4160
	ds_write_b32 v44, v75 offset:6240
	ds_write_b32 v44, v76 offset:8320
	ds_write_b32 v44, v77 offset:10400
	ds_write_b32 v44, v78 offset:12480
	ds_write_b32 v44, v79 offset:14560
	s_mul_hi_u32 s55, s32, s23
	s_mul_i32 s56, s55, s22
	s_sub_u32 s56, s32, s56
	s_lshl_b32 s57, s56, 6
	s_cmp_eq_u32 s29, 0
	s_cbranch_scc1 .Lcw_np_1
	s_lshl_b32 s57, s56, 7
	s_cmpk_lt_u32 s56, 44
	s_cbranch_scc1 .Lcw_np_1
	s_addk_i32 s57, -5600
.Lcw_np_1:
	s_mul_i32 s57, s57, s21
	s_lshl_b32 s55, s55, 7
	s_add_u32 s57, s57, s55
	s_add_u32 s52, s18, s57
	s_addc_u32 s53, s19, 0
	s_waitcnt lgkmcnt(0)
	s_barrier
	ds_read2_b32 v[46:47], v45 offset0:0 offset1:65
	ds_read2_b32 v[48:49], v45 offset0:16 offset1:81
	ds_read2_b32 v[50:51], v45 offset0:32 offset1:97
	ds_read2_b32 v[52:53], v45 offset0:48 offset1:113
	s_waitcnt lgkmcnt(3)
	v_cvt_pk_bf16_f32 v54, v46, v47
	global_store_dword v40, v54, s[52:53]
	s_waitcnt lgkmcnt(2)
	v_cvt_pk_bf16_f32 v55, v48, v49
	global_store_dword v41, v55, s[52:53]
	s_waitcnt lgkmcnt(1)
	v_cvt_pk_bf16_f32 v56, v50, v51
	global_store_dword v42, v56, s[52:53]
	s_waitcnt lgkmcnt(0)
	v_cvt_pk_bf16_f32 v57, v52, v53
	global_store_dword v43, v57, s[52:53]
	s_xor_b32 s34, s34, 0x4100
	s_addk_i32 s32, 0x100
	s_cmp_ge_u32 s32, s24
	s_cbranch_scc1 .Lcw_done
	s_min_u32 s54, s31, s25
	s_mul_hi_u32 s55, s54, s23
	s_mul_i32 s56, s55, s22
	s_sub_u32 s56, s54, s56
	s_mul_i32 s57, s55, s20
	s_lshl_b32 s56, s56, 8
	s_add_u32 s57, s57, s56
	s_add_u32 s48, s16, s57
	s_addc_u32 s49, s17, 0
	s_lshl_b32 s55, s55, 8
	s_add_u32 s50, s26, s55
	s_addc_u32 s51, s27, 0
	global_load_dword v72, v13, s[48:49]
	global_load_dword v73, v14, s[48:49]
	global_load_dword v74, v15, s[48:49]
	global_load_dword v75, v16, s[48:49]
	global_load_dword v76, v17, s[48:49]
	global_load_dword v77, v18, s[48:49]
	global_load_dword v78, v19, s[48:49]
	global_load_dword v79, v20, s[48:49]
	global_load_dword v96, v21, s[50:51]
	global_load_dword v97, v22, s[50:51]
	global_load_dword v98, v23, s[50:51]
	global_load_dword v99, v24, s[50:51]
	global_load_dword v100, v25, s[50:51]
	global_load_dword v101, v26, s[50:51]
	global_load_dword v102, v27, s[50:51]
	global_load_dword v103, v28, s[50:51]
	s_addk_i32 s31, 0x100
	s_waitcnt vmcnt(32)
	s_cmp_eq_u32 s28, 0
	s_cbranch_scc1 .Lcw_nogain_2
	v_mul_f32_e32 v80, v80, v104
	v_mul_f32_e32 v81, v81, v105
	v_mul_f32_e32 v82, v82, v106
	v_mul_f32_e32 v83, v83, v107
	v_mul_f32_e32 v84, v84, v108
	v_mul_f32_e32 v85, v85, v109
	v_mul_f32_e32 v86, v86, v110
	v_mul_f32_e32 v87, v87, v111
.Lcw_nogain_2:
	v_add_u32_e32 v44, s34, v29
	v_add_u32_e32 v45, s34, v30
	ds_write_b32 v44, v80
	ds_write_b32 v44, v81 offset:2080
	ds_write_b32 v44, v82 offset:4160
	ds_write_b32 v44, v83 offset:6240
	ds_write_b32 v44, v84 offset:8320
	ds_write_b32 v44, v85 offset:10400
	ds_write_b32 v44, v86 offset:12480
	ds_write_b32 v44, v87 offset:14560
	s_mul_hi_u32 s55, s32, s23
	s_mul_i32 s56, s55, s22
	s_sub_u32 s56, s32, s56
	s_lshl_b32 s57, s56, 6
	s_cmp_eq_u32 s29, 0
	s_cbranch_scc1 .Lcw_np_2
	s_lshl_b32 s57, s56, 7
	s_cmpk_lt_u32 s56, 44
	s_cbranch_scc1 .Lcw_np_2
	s_addk_i32 s57, -5600
.Lcw_np_2:
	s_mul_i32 s57, s57, s21
	s_lshl_b32 s55, s55, 7
	s_add_u32 s57, s57, s55
	s_add_u32 s52, s18, s57
	s_addc_u32 s53, s19, 0
	s_waitcnt lgkmcnt(0)
	s_barrier
	ds_read2_b32 v[46:47], v45 offset0:0 offset1:65
	ds_read2_b32 v[48:49], v45 offset0:16 offset1:81
	ds_read2_b32 v[50:51], v45 offset0:32 offset1:97
	ds_read2_b32 v[52:53], v45 offset0:48 offset1:113
	s_waitcnt lgkmcnt(3)
	v_cvt_pk_bf16_f32 v54, v46, v47
	global_store_dword v40, v54, s[52:53]
	s_waitcnt lgkmcnt(2)
	v_cvt_pk_bf16_f32 v55, v48, v49
	global_store_dword v41, v55, s[52:53]
	s_waitcnt lgkmcnt(1)
	v_cvt_pk_bf16_f32 v56, v50, v51
	global_store_dword v42, v56, s[52:53]
	s_waitcnt lgkmcnt(0)
	v_cvt_pk_bf16_f32 v57, v52, v53
	global_store_dword v43, v57, s[52:53]
	s_xor_b32 s34, s34, 0x4100
	s_addk_i32 s32, 0x100
	s_cmp_ge_u32 s32, s24
	s_cbranch_scc1 .Lcw_done
	s_branch .Lcw_loop
.Lcw_done:
	s_cmp_eq_u32 s30, 0
	s_cbranch_scc1 .Lcw_ret_0
	s_cmp_eq_u32 s30, 1
	s_cbranch_scc1 .Lcw_ret_1
	s_cmp_eq_u32 s30, 2
	s_cbranch_scc1 .Lcw_ret_2
	s_cmp_eq_u32 s30, 3
	s_cbranch_scc1 .Lcw_ret_3
	s_cmp_eq_u32 s30, 4
	s_cbranch_scc1 .Lcw_ret_4
	s_cmp_eq_u32 s30, 5
	s_cbranch_scc1 .Lcw_ret_5
	s_cmp_eq_u32 s30, 6
	s_cbranch_scc1 .Lcw_ret_6
	s_cmp_eq_u32 s30, 7
	s_cbranch_scc1 .Lcw_ret_7
	s_cmp_eq_u32 s30, 8
	s_cbranch_scc1 .Lcw_ret_8
	s_cmp_eq_u32 s30, 9
	s_cbranch_scc1 .Lcw_ret_9
	s_cmp_eq_u32 s30, 10
	s_cbranch_scc1 .Lcw_ret_10
	s_cmp_eq_u32 s30, 11
	s_cbranch_scc1 .Lcw_ret_11
	s_cmp_eq_u32 s30, 12
	s_cbranch_scc1 .Lcw_ret_12
	s_cmp_eq_u32 s30, 13
	s_cbranch_scc1 .Lcw_ret_13
	s_cmp_eq_u32 s30, 14
	s_cbranch_scc1 .Lcw_ret_14
	s_cmp_eq_u32 s30, 15
	s_cbranch_scc1 .Lcw_ret_15
	s_cmp_eq_u32 s30, 16
	s_cbranch_scc1 .Lcw_ret_16
	s_cmp_eq_u32 s30, 17
	s_cbranch_scc1 .Lcw_ret_17
	s_cmp_eq_u32 s30, 18
	s_cbranch_scc1 .Lcw_ret_18
	s_cmp_eq_u32 s30, 19
	s_cbranch_scc1 .Lcw_ret_19
	s_cmp_eq_u32 s30, 20
	s_cbranch_scc1 .Lcw_ret_20
	s_cmp_eq_u32 s30, 21
	s_cbranch_scc1 .Lcw_ret_21
	s_cmp_eq_u32 s30, 22
	s_cbranch_scc1 .Lcw_ret_22
	s_cmp_eq_u32 s30, 23
	s_cbranch_scc1 .Lcw_ret_23
	s_endpgm
